# attention: per-workgroup rotation of the chunk-group order (4 phases) to spread memory channels
# speedup vs baseline: 1.0058x; 1.0026x over previous
.LBB0_419:
	v_writelane_b32 v255, s89, 39
	v_writelane_b32 v255, s88, 40
	v_writelane_b32 v255, s87, 41
	v_writelane_b32 v255, s86, 42
	s_or_b64 exec, exec, s[0:1]
	s_add_u32 s84, s78, 0x27c00000
	s_addc_u32 s85, s79, 0
	s_add_u32 s54, s78, 0x2fc40000
	s_addc_u32 s55, s79, 0
	s_cmpk_gt_i32 s80, 0x7ff
	s_waitcnt lgkmcnt(0)
	s_barrier
	v_mbcnt_lo_u32_b32 v0, -1, 0
	v_mbcnt_hi_u32_b32 v0, -1, v0
	s_cbranch_scc1 .LBB0_469
	s_lshl_b32 s0, s94, 12
	s_add_i32 s3, s0, 0
	v_readlane_b32 s0, v255, 32
	s_bfe_u32 s43, s0, 0x30006
	s_lshr_b32 s100, s2, 3
	s_and_b32 s100, s100, 3
	s_lshl_b32 s100, s100, 4
	s_add_i32 s101, s43, s100
	s_lshl_b32 s0, s101, 16
	s_mov_b32 s57, 0
	s_lshl_b32 s62, s0, 1
	s_mov_b32 s66, 2.0
	s_mov_b32 s68, 0x41000000
	s_mov_b32 s70, 0x41200000
	s_mov_b32 s72, 0x41800000
	s_mov_b32 s96, 0x41900000
	s_mov_b32 s44, 0x41c00000
	s_mov_b32 s50, 0x41d00000
	s_lshl_b32 s60, s101, 12
	s_mov_b32 s61, s57
	s_xor_b32 s86, s43, 15
	s_mov_b32 s64, s62
	s_mov_b32 s65, s57
	v_mov_b32_e32 v161, 0
	s_mov_b32 s67, 0x40400000
	s_mov_b32 s69, 0x41100000
	s_mov_b32 s71, 0x41300000
	s_mov_b32 s73, 0x41880000
	s_mov_b32 s97, 0x41980000
	s_mov_b32 s45, 0x41c80000
	s_mov_b32 s51, 0x41d80000
	v_mbcnt_hi_u32_b32 v188, -1, v254
	v_mov_b32_e32 v189, 0xff800000
	s_mov_b32 s87, s80
	s_branch .LBB0_422

.LBB0_424:
	s_lshl_b32 s91, s42, 3
	s_add_i32 s91, s91, s100
	s_and_b32 s56, s91, 48
	s_bitcmp0_b32 s42, 0
	s_cselect_b64 s[0:1], -1, 0
	s_and_b64 s[92:93], s[0:1], exec
	s_cselect_b32 s90, s43, s86
	s_or_b32 s92, s90, s56
	v_mov_b32_e32 v16, 0
	s_waitcnt vmcnt(17)
	v_mov_b32_e32 v153, 1.0
	s_mov_b32 s90, s92
	v_mov_b32_e32 v17, v16
	v_mov_b32_e32 v18, v16
	v_mov_b32_e32 v19, v16
	v_mov_b32_e32 v20, v16
	v_mov_b32_e32 v21, v16
	v_mov_b32_e32 v22, v16
	v_mov_b32_e32 v23, v16
	v_mov_b32_e32 v24, v16
	v_mov_b32_e32 v25, v16
	v_mov_b32_e32 v26, v16
	v_mov_b32_e32 v27, v16
	v_mov_b32_e32 v28, v16
	v_mov_b32_e32 v29, v16
	v_mov_b32_e32 v30, v16
	v_mov_b32_e32 v31, v16
	v_mov_b32_e32 v0, v16
	s_waitcnt lgkmcnt(0)
	v_mov_b32_e32 v1, v16
	v_mov_b32_e32 v2, v16
	v_mov_b32_e32 v3, v16
	v_mov_b32_e32 v4, v16
	v_mov_b32_e32 v5, v16
	v_mov_b32_e32 v6, v16
	v_mov_b32_e32 v7, v16
	v_mov_b32_e32 v8, v16
	v_mov_b32_e32 v9, v16
	v_mov_b32_e32 v10, v16
	v_mov_b32_e32 v11, v16
	v_mov_b32_e32 v12, v16
	v_mov_b32_e32 v13, v16
	v_mov_b32_e32 v14, v16
	v_mov_b32_e32 v15, v16

.LBB0_433:
	s_cmp_eq_u32 s42, 7
	s_cbranch_scc1 .LBB0_435
	s_add_i32 s91, s91, 8
	s_and_b32 s56, s91, 0x30
	s_and_b64 s[0:1], s[0:1], exec
	s_cselect_b32 s0, s86, s43
	s_or_b32 s0, s56, s0
	s_lshl_b32 s56, s0, 17
	v_lshl_add_u64 v[32:33], v[128:129], 0, s[56:57]
	s_lshl_b32 s56, s0, 12
	global_load_dwordx4 v[48:51], v[32:33], off offset:2048
	global_load_dwordx4 v[52:55], v[32:33], off offset:2080
	global_load_dwordx4 v[56:59], v[32:33], off offset:2112
	global_load_dwordx4 v[60:63], v[32:33], off offset:2144
	v_lshl_add_u64 v[32:33], v[132:133], 0, s[56:57]
	global_load_dwordx4 v[64:67], v[32:33], off
	global_load_dwordx4 v[68:71], v[32:33], off offset:1024
	global_load_dwordx4 v[72:75], v[32:33], off offset:2048
	global_load_dwordx4 v[80:83], v[32:33], off offset:3072
	v_lshl_add_u64 v[32:33], v[130:131], 0, s[56:57]
	global_load_dwordx4 v[76:79], v[32:33], off
	global_load_dwordx4 v[84:87], v[32:33], off offset:1024
	global_load_dwordx4 v[88:91], v[32:33], off offset:2048
	global_load_dwordx4 v[92:95], v[32:33], off offset:3072

.LBB0_445:
	s_lshl_b32 s10, s8, 3
	s_add_i32 s10, s10, s100
	s_and_b32 s9, s10, 48
	s_bitcmp0_b32 s8, 0
	s_cselect_b64 s[6:7], -1, 0
	s_and_b64 s[0:1], s[6:7], exec
	s_cselect_b32 s0, s43, s86
	s_or_b32 s11, s0, s9
	v_sub_u32_e64 v0, s11, 4 clamp
	s_lshl_b32 s9, s11, 5
	v_readfirstlane_b32 s12, v0
	v_mov_b32_e32 v0, 0
	v_or_b32_e32 v218, s9, v193
	s_mov_b32 s13, s11
	v_mov_b32_e32 v219, v194
	v_mov_b32_e32 v220, v160
	v_mov_b32_e32 v1, v0
	v_mov_b32_e32 v2, v0
	s_waitcnt lgkmcnt(0)
	v_mov_b32_e32 v3, v0
	v_mov_b32_e32 v4, v0
	v_mov_b32_e32 v5, v0
	v_mov_b32_e32 v6, v0
	v_mov_b32_e32 v7, v0
	v_mov_b32_e32 v8, v0
	v_mov_b32_e32 v9, v0
	v_mov_b32_e32 v10, v0
	v_mov_b32_e32 v11, v0
	v_mov_b32_e32 v12, v0
	v_mov_b32_e32 v13, v0
	v_mov_b32_e32 v14, v0
	v_mov_b32_e32 v15, v0
	v_mov_b32_e32 v16, v0
	v_mov_b32_e32 v17, v0
	v_mov_b32_e32 v18, v0
	v_mov_b32_e32 v19, v0
	v_mov_b32_e32 v20, v0
	v_mov_b32_e32 v21, v0
	v_mov_b32_e32 v22, v0
	v_mov_b32_e32 v23, v0
	v_mov_b32_e32 v24, v0
	v_mov_b32_e32 v25, v0
	v_mov_b32_e32 v26, v0
	v_mov_b32_e32 v27, v0
	v_mov_b32_e32 v28, v0
	v_mov_b32_e32 v29, v0
	v_mov_b32_e32 v30, v0
	v_mov_b32_e32 v31, v0
	v_mov_b32_e32 v32, v0
	v_mov_b32_e32 v33, v0
	v_mov_b32_e32 v34, v0
	v_mov_b32_e32 v35, v0
	v_mov_b32_e32 v36, v0
	v_mov_b32_e32 v37, v0
	v_mov_b32_e32 v38, v0
	v_mov_b32_e32 v39, v0
	v_mov_b32_e32 v40, v0
	v_mov_b32_e32 v41, v0
	v_mov_b32_e32 v42, v0
	v_mov_b32_e32 v43, v0
	v_mov_b32_e32 v44, v0
	v_mov_b32_e32 v45, v0
	v_mov_b32_e32 v46, v0
	v_mov_b32_e32 v47, v0
	v_mov_b32_e32 v48, v0
	v_mov_b32_e32 v49, v0
	v_mov_b32_e32 v50, v0
	v_mov_b32_e32 v51, v0
	v_mov_b32_e32 v52, v0
	v_mov_b32_e32 v53, v0
	v_mov_b32_e32 v54, v0
	v_mov_b32_e32 v55, v0
	v_mov_b32_e32 v56, v0
	v_mov_b32_e32 v57, v0
	v_mov_b32_e32 v58, v0
	v_mov_b32_e32 v59, v0
	v_mov_b32_e32 v60, v0
	v_mov_b32_e32 v61, v0
	v_mov_b32_e32 v62, v0
	v_mov_b32_e32 v63, v0

.LBB0_459:
	v_mov_b32_e32 v32, v219
	s_nop 1
	v_permlane32_swap_b32_e32 v219, v32
	v_add_f32_e32 v32, v219, v32
	v_div_scale_f32 v33, s[0:1], v32, v32, 1.0
	v_rcp_f32_e32 v34, v33
	s_cmp_eq_u32 s8, 7
	v_fma_f32 v35, -v33, v34, 1.0
	v_fmac_f32_e32 v34, v35, v34
	v_div_scale_f32 v35, vcc, 1.0, v32, 1.0
	v_mul_f32_e32 v36, v35, v34
	v_fma_f32 v37, -v33, v36, v35
	v_fmac_f32_e32 v36, v37, v34
	v_fma_f32 v33, -v33, v36, v35
	v_div_fmas_f32 v33, v33, v34, v36
	v_div_fixup_f32 v32, v33, v32, 1.0
	ds_bpermute_b32 v47, v197, v32
	ds_bpermute_b32 v46, v198, v32
	ds_bpermute_b32 v45, v199, v32
	ds_bpermute_b32 v44, v200, v32
	ds_bpermute_b32 v43, v201, v32
	ds_bpermute_b32 v42, v202, v32
	ds_bpermute_b32 v41, v203, v32
	ds_bpermute_b32 v40, v204, v32
	ds_bpermute_b32 v39, v205, v32
	ds_bpermute_b32 v38, v206, v32
	ds_bpermute_b32 v37, v207, v32
	ds_bpermute_b32 v36, v208, v32
	ds_bpermute_b32 v35, v209, v32
	ds_bpermute_b32 v34, v210, v32
	ds_bpermute_b32 v33, v211, v32
	ds_bpermute_b32 v32, v212, v32
	s_cbranch_scc1 .LBB0_461
	s_add_i32 s10, s10, 8
	s_and_b32 s10, s10, 0x30
	s_and_b64 s[0:1], s[6:7], exec
	s_cselect_b32 s0, s86, s43
	s_or_b32 s0, s10, s0
	s_lshl_b32 s56, s0, 17
	v_lshl_add_u64 v[48:49], v[164:165], 0, s[56:57]
	s_lshl_b32 s56, s0, 12
	global_load_dwordx4 v[80:83], v[48:49], off
	global_load_dwordx4 v[84:87], v[48:49], off offset:32
	global_load_dwordx4 v[88:91], v[48:49], off offset:64
	global_load_dwordx4 v[92:95], v[48:49], off offset:96
	v_lshl_add_u64 v[48:49], v[176:177], 0, s[56:57]
	global_load_dwordx4 v[96:99], v[48:49], off
	global_load_dwordx4 v[100:103], v[48:49], off offset:1024
	global_load_dwordx4 v[112:115], v[48:49], off offset:2048
	global_load_dwordx4 v[124:127], v[48:49], off offset:3072
	v_lshl_add_u64 v[48:49], v[162:163], 0, s[56:57]
	global_load_dwordx4 v[104:107], v[48:49], off
	global_load_dwordx4 v[108:111], v[48:49], off offset:1024
	global_load_dwordx4 v[116:119], v[48:49], off offset:2048
	global_load_dwordx4 v[120:123], v[48:49], off offset:3072

	.amdhsa_kernel _Z10hybrid_fwd4Args
		.amdhsa_group_segment_fixed_size 0
		.amdhsa_private_segment_fixed_size 0
		.amdhsa_kernarg_size 400
		.amdhsa_user_sgpr_count 2
		.amdhsa_user_sgpr_dispatch_ptr 0
		.amdhsa_user_sgpr_queue_ptr 0
		.amdhsa_user_sgpr_kernarg_segment_ptr 1
		.amdhsa_user_sgpr_dispatch_id 0
		.amdhsa_user_sgpr_kernarg_preload_length 0
		.amdhsa_user_sgpr_kernarg_preload_offset 0
		.amdhsa_user_sgpr_private_segment_size 0
		.amdhsa_uses_dynamic_stack 0
		.amdhsa_enable_private_segment 0
		.amdhsa_system_sgpr_workgroup_id_x 1
		.amdhsa_system_sgpr_workgroup_id_y 0
		.amdhsa_system_sgpr_workgroup_id_z 0
		.amdhsa_system_sgpr_workgroup_info 0
		.amdhsa_system_vgpr_workitem_id 2
		.amdhsa_next_free_vgpr 256
		.amdhsa_next_free_sgpr 102
		.amdhsa_accum_offset 256
		.amdhsa_reserve_vcc 1
		.amdhsa_float_round_mode_32 0
		.amdhsa_float_round_mode_16_64 0
		.amdhsa_float_denorm_mode_32 3
		.amdhsa_float_denorm_mode_16_64 3
		.amdhsa_dx10_clamp 1
		.amdhsa_ieee_mode 1
		.amdhsa_fp16_overflow 0
		.amdhsa_tg_split 0
		.amdhsa_exception_fp_ieee_invalid_op 0
		.amdhsa_exception_fp_denorm_src 0
		.amdhsa_exception_fp_ieee_div_zero 0
		.amdhsa_exception_fp_ieee_overflow 0
		.amdhsa_exception_fp_ieee_underflow 0
		.amdhsa_exception_fp_ieee_inexact 0
		.amdhsa_exception_int_div_zero 0
	.end_amdhsa_kernel

amdhsa.kernels:
  - .agpr_count:     0
    .args:
      - .offset:         0
        .size:           144
        .value_kind:     by_value
      - .offset:         144
        .size:           4
        .value_kind:     hidden_block_count_x
      - .offset:         148
        .size:           4
        .value_kind:     hidden_block_count_y
      - .offset:         152
        .size:           4
        .value_kind:     hidden_block_count_z
      - .offset:         156
        .size:           2
        .value_kind:     hidden_group_size_x
      - .offset:         158
        .size:           2
        .value_kind:     hidden_group_size_y
      - .offset:         160
        .size:           2
        .value_kind:     hidden_group_size_z
      - .offset:         162
        .size:           2
        .value_kind:     hidden_remainder_x
      - .offset:         164
        .size:           2
        .value_kind:     hidden_remainder_y
      - .offset:         166
        .size:           2
        .value_kind:     hidden_remainder_z
      - .offset:         184
        .size:           8
        .value_kind:     hidden_global_offset_x
      - .offset:         192
        .size:           8
        .value_kind:     hidden_global_offset_y
      - .offset:         200
        .size:           8
        .value_kind:     hidden_global_offset_z
      - .offset:         208
        .size:           2
        .value_kind:     hidden_grid_dims
      - .offset:         232
        .size:           8
        .value_kind:     hidden_multigrid_sync_arg
      - .offset:         264
        .size:           4
        .value_kind:     hidden_dynamic_lds_size
    .group_segment_fixed_size: 0
    .kernarg_segment_align: 8
    .kernarg_segment_size: 400
    .language:       OpenCL C
    .language_version:
      - 2
      - 0
    .max_flat_workgroup_size: 512
    .name:           _Z10hybrid_fwd4Args
    .private_segment_fixed_size: 0
    .sgpr_count:     108
    .sgpr_spill_count: 45
    .symbol:         _Z10hybrid_fwd4Args.kd
    .uniform_work_group_size: 1
    .uses_dynamic_stack: false
    .vgpr_count:     256
    .vgpr_spill_count: 0
    .wavefront_size: 64
